# kernel end: wave 0 of one workgroup per XCD issues an un-waited L2 write-back before s_endpgm
# baseline (speedup 1.0000x reference)
.LBB0_1152:
	s_cmp_gt_u32 s2, 7
	s_cbranch_scc1 .Lend_nowb
	v_readfirstlane_b32 s100, v0
	s_cmp_gt_u32 s100, 63
	s_cbranch_scc1 .Lend_nowb
	buffer_wbl2 sc1
